# layer 1: chain CUs take 3 tiles, CUs 224-255 take a ninth (layer 0 unchanged)
# speedup vs baseline: 1.0008x; 1.0008x over previous
;     __device__ __forceinline__ bool next(int i, Unit& u) const {
;     ...
;         if (mode == 0) { L = i * G + c; if (L >= nwg) return false; }
;         else if (c >= 32) { if (i < 8) L = i * 224 + (c - 32); else if (i == 8 && c < 96) L = 1984 + (c - 32); else return false; }
;         else { if (i < 6) L = 1792 + i * 32 + c; else return false; }
.LBB0_412:
	v_readlane_b32 s14, v254, 9
	v_readlane_b32 s15, v254, 10
	s_add_i32 s40, s2, 1
	s_and_b64 vcc, exec, s[14:15]
	s_cbranch_vccz .LBB0_415
	s_mov_b64 s[26:27], 0
	v_readlane_b32 s3, v255, 35
	s_sub_i32 s3, 3, s3
	s_cmp_lt_u32 s2, s3
	s_mov_b64 s[14:15], 0
	s_cbranch_scc0 .LBB0_416
	s_lshl_b32 s3, s40, 5
	v_readlane_b32 s14, v254, 22
	s_add_i32 s3, s14, s3
	s_mov_b64 s[14:15], -1
	s_branch .LBB0_416

;     __device__ __forceinline__ bool next(int i, Unit& u) const {
;     ...
;         else if (c >= 32) { if (i < 8) L = i * 224 + (c - 32); else if (i == 8 && c < 96) L = 1984 + (c - 32); else return false; }
.Lsched_layer1:
	s_cmp_eq_u32 s40, 8
	s_cbranch_scc0 .LBB0_421
	s_cmp_ge_u32 s69, 160
	s_cbranch_scc0 .LBB0_421
	s_add_i32 s3, s3, -192
	s_mov_b64 s[14:15], -1
	s_cmp_lt_u32 s69, 224
	s_cbranch_scc1 .LBB0_421
	s_add_i32 s3, s3, -96
	s_branch .LBB0_421
